# P1 and P9 GEMM epilogues staged through LDS so output stores are row-contiguous dwordx4 instead of one row per lane
# speedup vs baseline: 1.0486x; 1.0169x over previous
; __device__ void phase_inproj(const Params& p, char* lds) {
;     ...
;     gemm_mainloop<true>(hb + (size_t)m0 * LDH, LDH, wt + (size_t)n0 * LDH, LDH, DM, acc, lds, 2 * ((mt + nt) & 7));
; #pragma unroll
;     for (int i = 0; i < 2; ++i)
; #pragma unroll
;       for (int j = 0; j < 2; ++j) {
;         const int tok = m0 + wr * 64 + i * 32 + l31; const int cb = n0 + wc * 64 + j * 32;
;         if (nt < 8) {
;           st_bf16_sw((bf16_t*)(ws + W_C) + (size_t)tok * LDH + cb, acc[i][j], hh, 0.125f * LOG2E);
;         } else if (nt < 16) {
;           st_f32_sw((samp ? p.out + O_KS + (size_t)(tok - TP) * 1024 : p.out + O_KP + (size_t)tok * 1024) + (cb - 1024), acc[i][j], hh);
;           st_bf16_sw((bf16_t*)(ws + W_D) + (size_t)keyrow_of_token(tok) * LDH + (cb - 1024), acc[i][j], hh, 1.f);
;         } else if (nt < 26) {
;           st_f32_sw((float*)(ws + F_ZCQ) + (size_t)tok * 256 + (cb - 3072), acc[i][j], hh);
;         } else if (nt == 26) {
;           st_f32_sw((float*)(ws + F_ZCKV) + (size_t)tok * 128 + (cb - 3328), acc[i][j], hh);
;         } else if (nt == 27) {
;           if (cb == 3456) st_f32_sw((float*)(ws + F_ZKR) + (size_t)tok * 32, acc[i][j], hh);
;         } else {
;           f32x16 sg;
; #pragma unroll
;           for (int r = 0; r < 16; ++r) sg[r] = __builtin_amdgcn_rcpf(1.f + __expf(-acc[i][j][r]));
;           st_bf16_sw((bf16_t*)(p.out + O_Y) + (size_t)tok * 2048 + (cb - 3584), sg, hh, 1.f);
;         }
.LBB0_180:
	s_cmp_eq_u32 s51, 27
	s_cbranch_scc1 .Lp1_old
	v_and_b32_e32 v165, 63, v181
	v_lshrrev_b32_e32 v164, 6, v181
	v_and_b32_e32 v138, 31, v165
	v_lshrrev_b32_e32 v139, 5, v165
	v_mul_u32_u24_e32 v138, 0x110, v138
	v_lshlrev_b32_e32 v139, 4, v139
	v_mul_u32_u24_e32 v140, 0x2200, v164
	v_add3_u32 v138, v138, v139, v140
	v_add_u32_e32 v138, 0x8000, v138
	v_add_u32_e32 v139, 0x8000, v140
	v_lshrrev_b32_e32 v140, 3, v165
	v_and_b32_e32 v141, 7, v165
	v_mul_u32_u24_e32 v165, 0x110, v140
	v_add_u32_e32 v139, v139, v165
	v_lshl_add_u32 v139, v141, 5, v139
	s_cmp_lt_u32 s51, 8
	s_cbranch_scc1 .Lp1_q
	s_cmp_lt_u32 s51, 16
	s_cbranch_scc1 .Lp1_k
	s_cmp_lt_u32 s51, 26
	s_cbranch_scc1 .Lp1_zcq
	s_cmp_eq_u32 s51, 26
	s_cbranch_scc1 .Lp1_zckv
	v_mul_f32_e32 v48, 0xbfb8aa3b, v48
	v_mul_f32_e32 v49, 0xbfb8aa3b, v49
	v_mul_f32_e32 v50, 0xbfb8aa3b, v50
	v_mul_f32_e32 v51, 0xbfb8aa3b, v51
	v_exp_f32_e32 v48, v48
	v_exp_f32_e32 v49, v49
	v_exp_f32_e32 v50, v50
	v_exp_f32_e32 v51, v51
	v_add_f32_e32 v48, 1.0, v48
	v_add_f32_e32 v49, 1.0, v49
	v_add_f32_e32 v50, 1.0, v50
	v_add_f32_e32 v51, 1.0, v51
	v_rcp_f32_e32 v48, v48
	v_rcp_f32_e32 v49, v49
	v_rcp_f32_e32 v50, v50
	v_rcp_f32_e32 v51, v51
	v_mul_f32_e32 v52, 0xbfb8aa3b, v52
	v_mul_f32_e32 v53, 0xbfb8aa3b, v53
	v_mul_f32_e32 v54, 0xbfb8aa3b, v54
	v_mul_f32_e32 v55, 0xbfb8aa3b, v55
	v_exp_f32_e32 v52, v52
	v_exp_f32_e32 v53, v53
	v_exp_f32_e32 v54, v54
	v_exp_f32_e32 v55, v55
	v_add_f32_e32 v52, 1.0, v52
	v_add_f32_e32 v53, 1.0, v53
	v_add_f32_e32 v54, 1.0, v54
	v_add_f32_e32 v55, 1.0, v55
	v_rcp_f32_e32 v52, v52
	v_rcp_f32_e32 v53, v53
	v_rcp_f32_e32 v54, v54
	v_rcp_f32_e32 v55, v55
	v_mul_f32_e32 v56, 0xbfb8aa3b, v56
	v_mul_f32_e32 v57, 0xbfb8aa3b, v57
	v_mul_f32_e32 v58, 0xbfb8aa3b, v58
	v_mul_f32_e32 v59, 0xbfb8aa3b, v59
	v_exp_f32_e32 v56, v56
	v_exp_f32_e32 v57, v57
	v_exp_f32_e32 v58, v58
	v_exp_f32_e32 v59, v59
	v_add_f32_e32 v56, 1.0, v56
	v_add_f32_e32 v57, 1.0, v57
	v_add_f32_e32 v58, 1.0, v58
	v_add_f32_e32 v59, 1.0, v59
	v_rcp_f32_e32 v56, v56
	v_rcp_f32_e32 v57, v57
	v_rcp_f32_e32 v58, v58
	v_rcp_f32_e32 v59, v59
	v_mul_f32_e32 v60, 0xbfb8aa3b, v60
	v_mul_f32_e32 v61, 0xbfb8aa3b, v61
	v_mul_f32_e32 v62, 0xbfb8aa3b, v62
	v_mul_f32_e32 v63, 0xbfb8aa3b, v63
	v_exp_f32_e32 v60, v60
	v_exp_f32_e32 v61, v61
	v_exp_f32_e32 v62, v62
	v_exp_f32_e32 v63, v63
	v_add_f32_e32 v60, 1.0, v60
	v_add_f32_e32 v61, 1.0, v61
	v_add_f32_e32 v62, 1.0, v62
	v_add_f32_e32 v63, 1.0, v63
	v_rcp_f32_e32 v60, v60
	v_rcp_f32_e32 v61, v61
	v_rcp_f32_e32 v62, v62
	v_rcp_f32_e32 v63, v63
	v_mul_f32_e32 v32, 0xbfb8aa3b, v32
	v_mul_f32_e32 v33, 0xbfb8aa3b, v33
	v_mul_f32_e32 v34, 0xbfb8aa3b, v34
	v_mul_f32_e32 v35, 0xbfb8aa3b, v35
	v_exp_f32_e32 v32, v32
	v_exp_f32_e32 v33, v33
	v_exp_f32_e32 v34, v34
	v_exp_f32_e32 v35, v35
	v_add_f32_e32 v32, 1.0, v32
	v_add_f32_e32 v33, 1.0, v33
	v_add_f32_e32 v34, 1.0, v34
	v_add_f32_e32 v35, 1.0, v35
	v_rcp_f32_e32 v32, v32
	v_rcp_f32_e32 v33, v33
	v_rcp_f32_e32 v34, v34
	v_rcp_f32_e32 v35, v35
	v_mul_f32_e32 v36, 0xbfb8aa3b, v36
	v_mul_f32_e32 v37, 0xbfb8aa3b, v37
	v_mul_f32_e32 v38, 0xbfb8aa3b, v38
	v_mul_f32_e32 v39, 0xbfb8aa3b, v39
	v_exp_f32_e32 v36, v36
	v_exp_f32_e32 v37, v37
	v_exp_f32_e32 v38, v38
	v_exp_f32_e32 v39, v39
	v_add_f32_e32 v36, 1.0, v36
	v_add_f32_e32 v37, 1.0, v37
	v_add_f32_e32 v38, 1.0, v38
	v_add_f32_e32 v39, 1.0, v39
	v_rcp_f32_e32 v36, v36
	v_rcp_f32_e32 v37, v37
	v_rcp_f32_e32 v38, v38
	v_rcp_f32_e32 v39, v39
	v_mul_f32_e32 v40, 0xbfb8aa3b, v40
	v_mul_f32_e32 v41, 0xbfb8aa3b, v41
	v_mul_f32_e32 v42, 0xbfb8aa3b, v42
	v_mul_f32_e32 v43, 0xbfb8aa3b, v43
	v_exp_f32_e32 v40, v40
	v_exp_f32_e32 v41, v41
	v_exp_f32_e32 v42, v42
	v_exp_f32_e32 v43, v43
	v_add_f32_e32 v40, 1.0, v40
	v_add_f32_e32 v41, 1.0, v41
	v_add_f32_e32 v42, 1.0, v42
	v_add_f32_e32 v43, 1.0, v43
	v_rcp_f32_e32 v40, v40
	v_rcp_f32_e32 v41, v41
	v_rcp_f32_e32 v42, v42
	v_rcp_f32_e32 v43, v43
	v_mul_f32_e32 v44, 0xbfb8aa3b, v44
	v_mul_f32_e32 v45, 0xbfb8aa3b, v45
	v_mul_f32_e32 v46, 0xbfb8aa3b, v46
	v_mul_f32_e32 v47, 0xbfb8aa3b, v47
	v_exp_f32_e32 v44, v44
	v_exp_f32_e32 v45, v45
	v_exp_f32_e32 v46, v46
	v_exp_f32_e32 v47, v47
	v_add_f32_e32 v44, 1.0, v44
	v_add_f32_e32 v45, 1.0, v45
	v_add_f32_e32 v46, 1.0, v46
	v_add_f32_e32 v47, 1.0, v47
	v_rcp_f32_e32 v44, v44
	v_rcp_f32_e32 v45, v45
	v_rcp_f32_e32 v46, v46
	v_rcp_f32_e32 v47, v47
	v_mul_f32_e32 v16, 0xbfb8aa3b, v16
	v_mul_f32_e32 v17, 0xbfb8aa3b, v17
	v_mul_f32_e32 v18, 0xbfb8aa3b, v18
	v_mul_f32_e32 v19, 0xbfb8aa3b, v19
	v_exp_f32_e32 v16, v16
	v_exp_f32_e32 v17, v17
	v_exp_f32_e32 v18, v18
	v_exp_f32_e32 v19, v19
	v_add_f32_e32 v16, 1.0, v16
	v_add_f32_e32 v17, 1.0, v17
	v_add_f32_e32 v18, 1.0, v18
	v_add_f32_e32 v19, 1.0, v19
	v_rcp_f32_e32 v16, v16
	v_rcp_f32_e32 v17, v17
	v_rcp_f32_e32 v18, v18
	v_rcp_f32_e32 v19, v19
	v_mul_f32_e32 v20, 0xbfb8aa3b, v20
	v_mul_f32_e32 v21, 0xbfb8aa3b, v21
	v_mul_f32_e32 v22, 0xbfb8aa3b, v22
	v_mul_f32_e32 v23, 0xbfb8aa3b, v23
	v_exp_f32_e32 v20, v20
	v_exp_f32_e32 v21, v21
	v_exp_f32_e32 v22, v22
	v_exp_f32_e32 v23, v23
	v_add_f32_e32 v20, 1.0, v20
	v_add_f32_e32 v21, 1.0, v21
	v_add_f32_e32 v22, 1.0, v22
	v_add_f32_e32 v23, 1.0, v23
	v_rcp_f32_e32 v20, v20
	v_rcp_f32_e32 v21, v21
	v_rcp_f32_e32 v22, v22
	v_rcp_f32_e32 v23, v23
	v_mul_f32_e32 v24, 0xbfb8aa3b, v24
	v_mul_f32_e32 v25, 0xbfb8aa3b, v25
	v_mul_f32_e32 v26, 0xbfb8aa3b, v26
	v_mul_f32_e32 v27, 0xbfb8aa3b, v27
	v_exp_f32_e32 v24, v24
	v_exp_f32_e32 v25, v25
	v_exp_f32_e32 v26, v26
	v_exp_f32_e32 v27, v27
	v_add_f32_e32 v24, 1.0, v24
	v_add_f32_e32 v25, 1.0, v25
	v_add_f32_e32 v26, 1.0, v26
	v_add_f32_e32 v27, 1.0, v27
	v_rcp_f32_e32 v24, v24
; __device__ void phase_inproj(const Params& p, char* lds) {
;     ...
;           f32x16 sg;
; #pragma unroll
;           for (int r = 0; r < 16; ++r) sg[r] = __builtin_amdgcn_rcpf(1.f + __expf(-acc[i][j][r]));
;           st_bf16_sw((bf16_t*)(p.out + O_Y) + (size_t)tok * 2048 + (cb - 3584), sg, hh, 1.f);
	v_rcp_f32_e32 v25, v25
	v_rcp_f32_e32 v26, v26
	v_rcp_f32_e32 v27, v27
	v_mul_f32_e32 v28, 0xbfb8aa3b, v28
	v_mul_f32_e32 v29, 0xbfb8aa3b, v29
	v_mul_f32_e32 v30, 0xbfb8aa3b, v30
	v_mul_f32_e32 v31, 0xbfb8aa3b, v31
	v_exp_f32_e32 v28, v28
	v_exp_f32_e32 v29, v29
	v_exp_f32_e32 v30, v30
	v_exp_f32_e32 v31, v31
	v_add_f32_e32 v28, 1.0, v28
	v_add_f32_e32 v29, 1.0, v29
	v_add_f32_e32 v30, 1.0, v30
	v_add_f32_e32 v31, 1.0, v31
	v_rcp_f32_e32 v28, v28
	v_rcp_f32_e32 v29, v29
	v_rcp_f32_e32 v30, v30
	v_rcp_f32_e32 v31, v31
	v_mul_f32_e32 v0, 0xbfb8aa3b, v0
	v_mul_f32_e32 v1, 0xbfb8aa3b, v1
	v_mul_f32_e32 v2, 0xbfb8aa3b, v2
	v_mul_f32_e32 v3, 0xbfb8aa3b, v3
	v_exp_f32_e32 v0, v0
	v_exp_f32_e32 v1, v1
	v_exp_f32_e32 v2, v2
	v_exp_f32_e32 v3, v3
	v_add_f32_e32 v0, 1.0, v0
	v_add_f32_e32 v1, 1.0, v1
	v_add_f32_e32 v2, 1.0, v2
	v_add_f32_e32 v3, 1.0, v3
	v_rcp_f32_e32 v0, v0
	v_rcp_f32_e32 v1, v1
	v_rcp_f32_e32 v2, v2
	v_rcp_f32_e32 v3, v3
	v_mul_f32_e32 v4, 0xbfb8aa3b, v4
	v_mul_f32_e32 v5, 0xbfb8aa3b, v5
	v_mul_f32_e32 v6, 0xbfb8aa3b, v6
	v_mul_f32_e32 v7, 0xbfb8aa3b, v7
	v_exp_f32_e32 v4, v4
	v_exp_f32_e32 v5, v5
	v_exp_f32_e32 v6, v6
	v_exp_f32_e32 v7, v7
	v_add_f32_e32 v4, 1.0, v4
	v_add_f32_e32 v5, 1.0, v5
	v_add_f32_e32 v6, 1.0, v6
	v_add_f32_e32 v7, 1.0, v7
	v_rcp_f32_e32 v4, v4
	v_rcp_f32_e32 v5, v5
	v_rcp_f32_e32 v6, v6
	v_rcp_f32_e32 v7, v7
	v_mul_f32_e32 v8, 0xbfb8aa3b, v8
	v_mul_f32_e32 v9, 0xbfb8aa3b, v9
	v_mul_f32_e32 v10, 0xbfb8aa3b, v10
	v_mul_f32_e32 v11, 0xbfb8aa3b, v11
	v_exp_f32_e32 v8, v8
	v_exp_f32_e32 v9, v9
	v_exp_f32_e32 v10, v10
	v_exp_f32_e32 v11, v11
	v_add_f32_e32 v8, 1.0, v8
	v_add_f32_e32 v9, 1.0, v9
	v_add_f32_e32 v10, 1.0, v10
	v_add_f32_e32 v11, 1.0, v11
	v_rcp_f32_e32 v8, v8
	v_rcp_f32_e32 v9, v9
	v_rcp_f32_e32 v10, v10
	v_rcp_f32_e32 v11, v11
	v_mul_f32_e32 v12, 0xbfb8aa3b, v12
	v_mul_f32_e32 v13, 0xbfb8aa3b, v13
	v_mul_f32_e32 v14, 0xbfb8aa3b, v14
	v_mul_f32_e32 v15, 0xbfb8aa3b, v15
	v_exp_f32_e32 v12, v12
	v_exp_f32_e32 v13, v13
	v_exp_f32_e32 v14, v14
	v_exp_f32_e32 v15, v15
	v_add_f32_e32 v12, 1.0, v12
	v_add_f32_e32 v13, 1.0, v13
	v_add_f32_e32 v14, 1.0, v14
	v_add_f32_e32 v15, 1.0, v15
	v_rcp_f32_e32 v12, v12
	v_rcp_f32_e32 v13, v13
	v_rcp_f32_e32 v14, v14
	v_rcp_f32_e32 v15, v15
	v_readlane_b32 s2, v248, 4
	v_readlane_b32 s3, v248, 5
	s_lshl_b32 s0, s53, 12
	s_sub_i32 s1, s54, 0xe00
	s_lshl_b32 s1, s1, 1
	s_add_i32 s0, s0, s1
	v_lshrrev_b32_e32 v169, 1, v164
	v_mul_u32_u24_e32 v169, 0x40000, v169
	v_mul_u32_u24_e32 v171, 0x1000, v140
	v_add_u32_e32 v169, v169, v171
	v_and_b32_e32 v171, 1, v164
	v_mul_u32_u24_e32 v171, 0x80, v171
	v_lshl_add_u32 v171, v141, 4, v171
	v_add3_u32 v169, v169, v171, s0
	ds_write_b128 v138, v[48:51] offset:0
	ds_write_b128 v138, v[52:55] offset:32
	ds_write_b128 v138, v[56:59] offset:64
	ds_write_b128 v138, v[60:63] offset:96
	ds_write_b128 v138, v[32:35] offset:128
	ds_write_b128 v138, v[36:39] offset:160
	ds_write_b128 v138, v[40:43] offset:192
	ds_write_b128 v138, v[44:47] offset:224
	s_waitcnt lgkmcnt(0)
	ds_read_b128 v[32:35], v139 offset:0
	ds_read_b128 v[36:39], v139 offset:16
	ds_read_b128 v[40:43], v139 offset:2176
	ds_read_b128 v[44:47], v139 offset:2192
	ds_read_b128 v[48:51], v139 offset:4352
	ds_read_b128 v[52:55], v139 offset:4368
	ds_read_b128 v[56:59], v139 offset:6528
	ds_read_b128 v[60:63], v139 offset:6544
	s_waitcnt lgkmcnt(6)
	v_cvt_pk_bf16_f32 v32, v32, v33
	v_cvt_pk_bf16_f32 v33, v34, v35
	v_cvt_pk_bf16_f32 v34, v36, v37
	v_cvt_pk_bf16_f32 v35, v38, v39
	global_store_dwordx4 v169, v[32:35], s[2:3]
	v_add_u32_e32 v169, 0x8000, v169
	s_waitcnt lgkmcnt(4)
	v_cvt_pk_bf16_f32 v40, v40, v41
	v_cvt_pk_bf16_f32 v41, v42, v43
	v_cvt_pk_bf16_f32 v42, v44, v45
	v_cvt_pk_bf16_f32 v43, v46, v47
	global_store_dwordx4 v169, v[40:43], s[2:3]
	v_add_u32_e32 v169, 0x8000, v169
	s_waitcnt lgkmcnt(2)
	v_cvt_pk_bf16_f32 v48, v48, v49
	v_cvt_pk_bf16_f32 v49, v50, v51
	v_cvt_pk_bf16_f32 v50, v52, v53
	v_cvt_pk_bf16_f32 v51, v54, v55
	global_store_dwordx4 v169, v[48:51], s[2:3]
	v_add_u32_e32 v169, 0x8000, v169
	s_waitcnt lgkmcnt(0)
	v_cvt_pk_bf16_f32 v56, v56, v57
	v_cvt_pk_bf16_f32 v57, v58, v59
	v_cvt_pk_bf16_f32 v58, v60, v61
	v_cvt_pk_bf16_f32 v59, v62, v63
	global_store_dwordx4 v169, v[56:59], s[2:3]
	v_add_u32_e32 v169, 0x8000, v169
	ds_write_b128 v138, v[16:19] offset:0
	ds_write_b128 v138, v[20:23] offset:32
	ds_write_b128 v138, v[24:27] offset:64
	ds_write_b128 v138, v[28:31] offset:96
	ds_write_b128 v138, v[0:3] offset:128
	ds_write_b128 v138, v[4:7] offset:160
	ds_write_b128 v138, v[8:11] offset:192
	ds_write_b128 v138, v[12:15] offset:224
	s_waitcnt lgkmcnt(0)
	ds_read_b128 v[0:3], v139 offset:0
	ds_read_b128 v[4:7], v139 offset:16
	ds_read_b128 v[8:11], v139 offset:2176
	ds_read_b128 v[12:15], v139 offset:2192
	ds_read_b128 v[16:19], v139 offset:4352
	ds_read_b128 v[20:23], v139 offset:4368
	ds_read_b128 v[24:27], v139 offset:6528
	ds_read_b128 v[28:31], v139 offset:6544
	s_waitcnt lgkmcnt(6)
	v_cvt_pk_bf16_f32 v0, v0, v1
	v_cvt_pk_bf16_f32 v1, v2, v3
	v_cvt_pk_bf16_f32 v2, v4, v5
	v_cvt_pk_bf16_f32 v3, v6, v7
	global_store_dwordx4 v169, v[0:3], s[2:3]
	v_add_u32_e32 v169, 0x8000, v169
	s_waitcnt lgkmcnt(4)
	v_cvt_pk_bf16_f32 v8, v8, v9
	v_cvt_pk_bf16_f32 v9, v10, v11
	v_cvt_pk_bf16_f32 v10, v12, v13
	v_cvt_pk_bf16_f32 v11, v14, v15
	global_store_dwordx4 v169, v[8:11], s[2:3]
	v_add_u32_e32 v169, 0x8000, v169
	s_waitcnt lgkmcnt(2)
	v_cvt_pk_bf16_f32 v16, v16, v17
	v_cvt_pk_bf16_f32 v17, v18, v19
	v_cvt_pk_bf16_f32 v18, v20, v21
	v_cvt_pk_bf16_f32 v19, v22, v23
	global_store_dwordx4 v169, v[16:19], s[2:3]
	v_add_u32_e32 v169, 0x8000, v169
	s_waitcnt lgkmcnt(0)
	v_cvt_pk_bf16_f32 v24, v24, v25
	v_cvt_pk_bf16_f32 v25, v26, v27
	v_cvt_pk_bf16_f32 v26, v28, v29
	v_cvt_pk_bf16_f32 v27, v30, v31
	global_store_dwordx4 v169, v[24:27], s[2:3]
	v_add_u32_e32 v169, 0x8000, v169
	s_branch .LBB0_260
; __device__ void phase_inproj(const Params& p, char* lds) {
;     ...
;         if (nt < 8) {
;           st_bf16_sw((bf16_t*)(ws + W_C) + (size_t)tok * LDH + cb, acc[i][j], hh, 0.125f * LOG2E);
.Lp1_q:
	s_mul_i32 s0, s53, 0x880
	s_lshl_b32 s1, s54, 1
	s_add_i32 s0, s0, s1
	s_add_i32 s0, s0, 0x5b7e000
	v_lshrrev_b32_e32 v169, 1, v164
	v_mul_u32_u24_e32 v169, 0x22000, v169
	v_mul_u32_u24_e32 v171, 0x880, v140
	v_add_u32_e32 v169, v169, v171
	v_and_b32_e32 v171, 1, v164
	v_mul_u32_u24_e32 v171, 0x80, v171
	v_lshl_add_u32 v171, v141, 4, v171
	v_add3_u32 v169, v169, v171, s0
	ds_write_b128 v138, v[48:51] offset:0
	ds_write_b128 v138, v[52:55] offset:32
	ds_write_b128 v138, v[56:59] offset:64
	ds_write_b128 v138, v[60:63] offset:96
	ds_write_b128 v138, v[32:35] offset:128
	ds_write_b128 v138, v[36:39] offset:160
	ds_write_b128 v138, v[40:43] offset:192
	ds_write_b128 v138, v[44:47] offset:224
	s_waitcnt lgkmcnt(0)
	ds_read_b128 v[32:35], v139 offset:0
	ds_read_b128 v[36:39], v139 offset:16
	ds_read_b128 v[40:43], v139 offset:2176
	ds_read_b128 v[44:47], v139 offset:2192
	ds_read_b128 v[48:51], v139 offset:4352
	ds_read_b128 v[52:55], v139 offset:4368
	ds_read_b128 v[56:59], v139 offset:6528
	ds_read_b128 v[60:63], v139 offset:6544
	s_waitcnt lgkmcnt(6)
	v_pk_mul_f32 v[32:33], v[32:33], s[26:27] op_sel_hi:[1,0]
	v_pk_mul_f32 v[34:35], v[34:35], s[26:27] op_sel_hi:[1,0]
	v_pk_mul_f32 v[36:37], v[36:37], s[26:27] op_sel_hi:[1,0]
	v_pk_mul_f32 v[38:39], v[38:39], s[26:27] op_sel_hi:[1,0]
	v_cvt_pk_bf16_f32 v32, v32, v33
	v_cvt_pk_bf16_f32 v33, v34, v35
	v_cvt_pk_bf16_f32 v34, v36, v37
	v_cvt_pk_bf16_f32 v35, v38, v39
	global_store_dwordx4 v169, v[32:35], s[96:97]
	v_add_u32_e32 v169, 0x4400, v169
	s_waitcnt lgkmcnt(4)
	v_pk_mul_f32 v[40:41], v[40:41], s[26:27] op_sel_hi:[1,0]
	v_pk_mul_f32 v[42:43], v[42:43], s[26:27] op_sel_hi:[1,0]
	v_pk_mul_f32 v[44:45], v[44:45], s[26:27] op_sel_hi:[1,0]
	v_pk_mul_f32 v[46:47], v[46:47], s[26:27] op_sel_hi:[1,0]
	v_cvt_pk_bf16_f32 v40, v40, v41
	v_cvt_pk_bf16_f32 v41, v42, v43
	v_cvt_pk_bf16_f32 v42, v44, v45
	v_cvt_pk_bf16_f32 v43, v46, v47
	global_store_dwordx4 v169, v[40:43], s[96:97]
	v_add_u32_e32 v169, 0x4400, v169
	s_waitcnt lgkmcnt(2)
	v_pk_mul_f32 v[48:49], v[48:49], s[26:27] op_sel_hi:[1,0]
	v_pk_mul_f32 v[50:51], v[50:51], s[26:27] op_sel_hi:[1,0]
	v_pk_mul_f32 v[52:53], v[52:53], s[26:27] op_sel_hi:[1,0]
	v_pk_mul_f32 v[54:55], v[54:55], s[26:27] op_sel_hi:[1,0]
	v_cvt_pk_bf16_f32 v48, v48, v49
	v_cvt_pk_bf16_f32 v49, v50, v51
	v_cvt_pk_bf16_f32 v50, v52, v53
	v_cvt_pk_bf16_f32 v51, v54, v55
	global_store_dwordx4 v169, v[48:51], s[96:97]
	v_add_u32_e32 v169, 0x4400, v169
	s_waitcnt lgkmcnt(0)
	v_pk_mul_f32 v[56:57], v[56:57], s[26:27] op_sel_hi:[1,0]
	v_pk_mul_f32 v[58:59], v[58:59], s[26:27] op_sel_hi:[1,0]
	v_pk_mul_f32 v[60:61], v[60:61], s[26:27] op_sel_hi:[1,0]
	v_pk_mul_f32 v[62:63], v[62:63], s[26:27] op_sel_hi:[1,0]
	v_cvt_pk_bf16_f32 v56, v56, v57
	v_cvt_pk_bf16_f32 v57, v58, v59
	v_cvt_pk_bf16_f32 v58, v60, v61
	v_cvt_pk_bf16_f32 v59, v62, v63
	global_store_dwordx4 v169, v[56:59], s[96:97]
	v_add_u32_e32 v169, 0x4400, v169
	ds_write_b128 v138, v[16:19] offset:0
	ds_write_b128 v138, v[20:23] offset:32
	ds_write_b128 v138, v[24:27] offset:64
	ds_write_b128 v138, v[28:31] offset:96
	ds_write_b128 v138, v[0:3] offset:128
	ds_write_b128 v138, v[4:7] offset:160
	ds_write_b128 v138, v[8:11] offset:192
	ds_write_b128 v138, v[12:15] offset:224
	s_waitcnt lgkmcnt(0)
	ds_read_b128 v[0:3], v139 offset:0
	ds_read_b128 v[4:7], v139 offset:16
	ds_read_b128 v[8:11], v139 offset:2176
	ds_read_b128 v[12:15], v139 offset:2192
	ds_read_b128 v[16:19], v139 offset:4352
	ds_read_b128 v[20:23], v139 offset:4368
	ds_read_b128 v[24:27], v139 offset:6528
	ds_read_b128 v[28:31], v139 offset:6544
	s_waitcnt lgkmcnt(6)
	v_pk_mul_f32 v[0:1], v[0:1], s[26:27] op_sel_hi:[1,0]
	v_pk_mul_f32 v[2:3], v[2:3], s[26:27] op_sel_hi:[1,0]
	v_pk_mul_f32 v[4:5], v[4:5], s[26:27] op_sel_hi:[1,0]
	v_pk_mul_f32 v[6:7], v[6:7], s[26:27] op_sel_hi:[1,0]
	v_cvt_pk_bf16_f32 v0, v0, v1
	v_cvt_pk_bf16_f32 v1, v2, v3
	v_cvt_pk_bf16_f32 v2, v4, v5
	v_cvt_pk_bf16_f32 v3, v6, v7
	global_store_dwordx4 v169, v[0:3], s[96:97]
	v_add_u32_e32 v169, 0x4400, v169
	s_waitcnt lgkmcnt(4)
	v_pk_mul_f32 v[8:9], v[8:9], s[26:27] op_sel_hi:[1,0]
	v_pk_mul_f32 v[10:11], v[10:11], s[26:27] op_sel_hi:[1,0]
	v_pk_mul_f32 v[12:13], v[12:13], s[26:27] op_sel_hi:[1,0]
	v_pk_mul_f32 v[14:15], v[14:15], s[26:27] op_sel_hi:[1,0]
	v_cvt_pk_bf16_f32 v8, v8, v9
	v_cvt_pk_bf16_f32 v9, v10, v11
	v_cvt_pk_bf16_f32 v10, v12, v13
	v_cvt_pk_bf16_f32 v11, v14, v15
	global_store_dwordx4 v169, v[8:11], s[96:97]
	v_add_u32_e32 v169, 0x4400, v169
	s_waitcnt lgkmcnt(2)
	v_pk_mul_f32 v[16:17], v[16:17], s[26:27] op_sel_hi:[1,0]
	v_pk_mul_f32 v[18:19], v[18:19], s[26:27] op_sel_hi:[1,0]
	v_pk_mul_f32 v[20:21], v[20:21], s[26:27] op_sel_hi:[1,0]
	v_pk_mul_f32 v[22:23], v[22:23], s[26:27] op_sel_hi:[1,0]
	v_cvt_pk_bf16_f32 v16, v16, v17
	v_cvt_pk_bf16_f32 v17, v18, v19
	v_cvt_pk_bf16_f32 v18, v20, v21
	v_cvt_pk_bf16_f32 v19, v22, v23
	global_store_dwordx4 v169, v[16:19], s[96:97]
	v_add_u32_e32 v169, 0x4400, v169
	s_waitcnt lgkmcnt(0)
	v_pk_mul_f32 v[24:25], v[24:25], s[26:27] op_sel_hi:[1,0]
	v_pk_mul_f32 v[26:27], v[26:27], s[26:27] op_sel_hi:[1,0]
	v_pk_mul_f32 v[28:29], v[28:29], s[26:27] op_sel_hi:[1,0]
	v_pk_mul_f32 v[30:31], v[30:31], s[26:27] op_sel_hi:[1,0]
	v_cvt_pk_bf16_f32 v24, v24, v25
	v_cvt_pk_bf16_f32 v25, v26, v27
	v_cvt_pk_bf16_f32 v26, v28, v29
	v_cvt_pk_bf16_f32 v27, v30, v31
	global_store_dwordx4 v169, v[24:27], s[96:97]
	v_add_u32_e32 v169, 0x4400, v169
	s_branch .LBB0_260
; __device__ __forceinline__ int keyrow_of_token(int t) {
;   if (t < TP) return t;
;   int ts = t - TP; return TP + (ts >> 6) * LKS + PAST + (ts & 63);
; }
; __device__ void phase_inproj(const Params& p, char* lds) {
;     ...
;         } else if (nt < 16) {
;           st_f32_sw((samp ? p.out + O_KS + (size_t)(tok - TP) * 1024 : p.out + O_KP + (size_t)tok * 1024) + (cb - 1024), acc[i][j], hh);
;           st_bf16_sw((bf16_t*)(ws + W_D) + (size_t)keyrow_of_token(tok) * LDH + (cb - 1024), acc[i][j], hh, 1.f);
.Lp1_k:
	v_and_b32_e32 v165, 63, v181
	v_lshrrev_b32_e32 v167, 4, v165
	v_and_b32_e32 v168, 15, v165
	v_mul_u32_u24_e32 v166, 0x2200, v164
	v_mul_u32_u24_e32 v165, 0x110, v167
	v_add_u32_e32 v166, v166, v165
	v_add_u32_e32 v166, 0x8000, v166
	v_lshl_add_u32 v166, v168, 4, v166
	v_readlane_b32 s2, v248, 4
	v_readlane_b32 s3, v248, 5
	s_cmpk_gt_i32 s52, 0xff
	s_cbranch_scc1 .Lp1_k_samp
	s_lshl_b32 s0, s53, 12
	s_add_i32 s0, s0, 0x8200000
	s_mul_i32 s1, s53, 0x880
	s_add_i32 s1, s1, 0xa08e000
	s_mov_b32 s34, 0x22000
	s_branch .Lp1_k_go
.Lp1_k_samp:
	s_sub_i32 s35, s53, 0x8000
	s_lshl_b32 s0, s35, 12
	s_add_i32 s0, s0, 0x19600000
	s_sub_i32 s35, s52, 0x100
	s_mul_i32 s1, s35, 0x8c4000
	s_add_i32 s1, s1, 0x4840000
	s_add_i32 s1, s1, 0xa08e000
	s_mov_b32 s34, 0x462000
.Lp1_k_go:
	s_sub_i32 s35, s54, 0x400
	s_lshl_b32 s35, s35, 2
	s_add_i32 s0, s0, s35
	s_lshr_b32 s35, s35, 1
	s_add_i32 s1, s1, s35
	v_lshrrev_b32_e32 v170, 1, v164
	v_mul_u32_u24_e32 v170, 0x40000, v170
	v_mul_u32_u24_e32 v171, 0x1000, v167
	v_add_u32_e32 v170, v170, v171
	v_and_b32_e32 v171, 1, v164
	v_mul_u32_u24_e32 v171, 0x100, v171
	v_lshl_add_u32 v171, v168, 4, v171
	v_add3_u32 v170, v170, v171, s0
	v_lshrrev_b32_e32 v169, 1, v164
	v_mul_lo_u32 v169, v169, s34
	v_mul_u32_u24_e32 v171, 0x880, v140
	v_add_u32_e32 v169, v169, v171
	v_and_b32_e32 v171, 1, v164
	v_mul_u32_u24_e32 v171, 0x80, v171
	v_lshl_add_u32 v171, v141, 4, v171
	v_add3_u32 v169, v169, v171, s1
	ds_write_b128 v138, v[48:51] offset:0
	ds_write_b128 v138, v[52:55] offset:32
	ds_write_b128 v138, v[56:59] offset:64
	ds_write_b128 v138, v[60:63] offset:96
	ds_write_b128 v138, v[32:35] offset:128
	ds_write_b128 v138, v[36:39] offset:160
	ds_write_b128 v138, v[40:43] offset:192
	ds_write_b128 v138, v[44:47] offset:224
	s_waitcnt lgkmcnt(0)
	ds_read_b128 v[32:35], v166 offset:0
	ds_read_b128 v[36:39], v166 offset:1088
	ds_read_b128 v[40:43], v166 offset:2176
	ds_read_b128 v[44:47], v166 offset:3264
	ds_read_b128 v[48:51], v166 offset:4352
	ds_read_b128 v[52:55], v166 offset:5440
	ds_read_b128 v[56:59], v166 offset:6528
	ds_read_b128 v[60:63], v166 offset:7616
	s_waitcnt lgkmcnt(7)
	global_store_dwordx4 v170, v[32:35], s[2:3]
	v_add_u32_e32 v170, 0x4000, v170
	s_waitcnt lgkmcnt(6)
	global_store_dwordx4 v170, v[36:39], s[2:3]
	v_add_u32_e32 v170, 0x4000, v170
	s_waitcnt lgkmcnt(5)
	global_store_dwordx4 v170, v[40:43], s[2:3]
	v_add_u32_e32 v170, 0x4000, v170
	s_waitcnt lgkmcnt(4)
	global_store_dwordx4 v170, v[44:47], s[2:3]
	v_add_u32_e32 v170, 0x4000, v170
	s_waitcnt lgkmcnt(3)
	global_store_dwordx4 v170, v[48:51], s[2:3]
	v_add_u32_e32 v170, 0x4000, v170
	s_waitcnt lgkmcnt(2)
	global_store_dwordx4 v170, v[52:55], s[2:3]
	v_add_u32_e32 v170, 0x4000, v170
	s_waitcnt lgkmcnt(1)
	global_store_dwordx4 v170, v[56:59], s[2:3]
	v_add_u32_e32 v170, 0x4000, v170
	s_waitcnt lgkmcnt(0)
	global_store_dwordx4 v170, v[60:63], s[2:3]
	v_add_u32_e32 v170, 0x4000, v170
	ds_read_b128 v[32:35], v139 offset:0
	ds_read_b128 v[36:39], v139 offset:16
	ds_read_b128 v[40:43], v139 offset:2176
	ds_read_b128 v[44:47], v139 offset:2192
	ds_read_b128 v[48:51], v139 offset:4352
	ds_read_b128 v[52:55], v139 offset:4368
	ds_read_b128 v[56:59], v139 offset:6528
	ds_read_b128 v[60:63], v139 offset:6544
	s_waitcnt lgkmcnt(6)
	v_cvt_pk_bf16_f32 v32, v32, v33
	v_cvt_pk_bf16_f32 v33, v34, v35
	v_cvt_pk_bf16_f32 v34, v36, v37
	v_cvt_pk_bf16_f32 v35, v38, v39
	global_store_dwordx4 v169, v[32:35], s[96:97]
	v_add_u32_e32 v169, 0x4400, v169
	s_waitcnt lgkmcnt(4)
	v_cvt_pk_bf16_f32 v40, v40, v41
	v_cvt_pk_bf16_f32 v41, v42, v43
	v_cvt_pk_bf16_f32 v42, v44, v45
	v_cvt_pk_bf16_f32 v43, v46, v47
	global_store_dwordx4 v169, v[40:43], s[96:97]
	v_add_u32_e32 v169, 0x4400, v169
	s_waitcnt lgkmcnt(2)
	v_cvt_pk_bf16_f32 v48, v48, v49
	v_cvt_pk_bf16_f32 v49, v50, v51
	v_cvt_pk_bf16_f32 v50, v52, v53
	v_cvt_pk_bf16_f32 v51, v54, v55
	global_store_dwordx4 v169, v[48:51], s[96:97]
	v_add_u32_e32 v169, 0x4400, v169
	s_waitcnt lgkmcnt(0)
	v_cvt_pk_bf16_f32 v56, v56, v57
	v_cvt_pk_bf16_f32 v57, v58, v59
	v_cvt_pk_bf16_f32 v58, v60, v61
	v_cvt_pk_bf16_f32 v59, v62, v63
	global_store_dwordx4 v169, v[56:59], s[96:97]
	v_add_u32_e32 v169, 0x4400, v169
	ds_write_b128 v138, v[16:19] offset:0
	ds_write_b128 v138, v[20:23] offset:32
	ds_write_b128 v138, v[24:27] offset:64
	ds_write_b128 v138, v[28:31] offset:96
	ds_write_b128 v138, v[0:3] offset:128
	ds_write_b128 v138, v[4:7] offset:160
	ds_write_b128 v138, v[8:11] offset:192
	ds_write_b128 v138, v[12:15] offset:224
	s_waitcnt lgkmcnt(0)
	ds_read_b128 v[0:3], v166 offset:0
	ds_read_b128 v[4:7], v166 offset:1088
	ds_read_b128 v[8:11], v166 offset:2176
	ds_read_b128 v[12:15], v166 offset:3264
	ds_read_b128 v[16:19], v166 offset:4352
	ds_read_b128 v[20:23], v166 offset:5440
	ds_read_b128 v[24:27], v166 offset:6528
	ds_read_b128 v[28:31], v166 offset:7616
	s_waitcnt lgkmcnt(7)
	global_store_dwordx4 v170, v[0:3], s[2:3]
	v_add_u32_e32 v170, 0x4000, v170
	s_waitcnt lgkmcnt(6)
	global_store_dwordx4 v170, v[4:7], s[2:3]
	v_add_u32_e32 v170, 0x4000, v170
	s_waitcnt lgkmcnt(5)
	global_store_dwordx4 v170, v[8:11], s[2:3]
	v_add_u32_e32 v170, 0x4000, v170
	s_waitcnt lgkmcnt(4)
	global_store_dwordx4 v170, v[12:15], s[2:3]
	v_add_u32_e32 v170, 0x4000, v170
	s_waitcnt lgkmcnt(3)
	global_store_dwordx4 v170, v[16:19], s[2:3]
	v_add_u32_e32 v170, 0x4000, v170
	s_waitcnt lgkmcnt(2)
	global_store_dwordx4 v170, v[20:23], s[2:3]
	v_add_u32_e32 v170, 0x4000, v170
	s_waitcnt lgkmcnt(1)
	global_store_dwordx4 v170, v[24:27], s[2:3]
	v_add_u32_e32 v170, 0x4000, v170
	s_waitcnt lgkmcnt(0)
	global_store_dwordx4 v170, v[28:31], s[2:3]
	v_add_u32_e32 v170, 0x4000, v170
	ds_read_b128 v[0:3], v139 offset:0
	ds_read_b128 v[4:7], v139 offset:16
	ds_read_b128 v[8:11], v139 offset:2176
	ds_read_b128 v[12:15], v139 offset:2192
	ds_read_b128 v[16:19], v139 offset:4352
	ds_read_b128 v[20:23], v139 offset:4368
	ds_read_b128 v[24:27], v139 offset:6528
	ds_read_b128 v[28:31], v139 offset:6544
	s_waitcnt lgkmcnt(6)
	v_cvt_pk_bf16_f32 v0, v0, v1
	v_cvt_pk_bf16_f32 v1, v2, v3
	v_cvt_pk_bf16_f32 v2, v4, v5
	v_cvt_pk_bf16_f32 v3, v6, v7
	global_store_dwordx4 v169, v[0:3], s[96:97]
	v_add_u32_e32 v169, 0x4400, v169
	s_waitcnt lgkmcnt(4)
	v_cvt_pk_bf16_f32 v8, v8, v9
	v_cvt_pk_bf16_f32 v9, v10, v11
	v_cvt_pk_bf16_f32 v10, v12, v13
	v_cvt_pk_bf16_f32 v11, v14, v15
	global_store_dwordx4 v169, v[8:11], s[96:97]
	v_add_u32_e32 v169, 0x4400, v169
	s_waitcnt lgkmcnt(2)
	v_cvt_pk_bf16_f32 v16, v16, v17
	v_cvt_pk_bf16_f32 v17, v18, v19
	v_cvt_pk_bf16_f32 v18, v20, v21
	v_cvt_pk_bf16_f32 v19, v22, v23
	global_store_dwordx4 v169, v[16:19], s[96:97]
	v_add_u32_e32 v169, 0x4400, v169
	s_waitcnt lgkmcnt(0)
	v_cvt_pk_bf16_f32 v24, v24, v25
	v_cvt_pk_bf16_f32 v25, v26, v27
	v_cvt_pk_bf16_f32 v26, v28, v29
	v_cvt_pk_bf16_f32 v27, v30, v31
	global_store_dwordx4 v169, v[24:27], s[96:97]
	v_add_u32_e32 v169, 0x4400, v169
	s_branch .LBB0_260
; __device__ void phase_inproj(const Params& p, char* lds) {
;     ...
;         } else if (nt < 26) {
;           st_f32_sw((float*)(ws + F_ZCQ) + (size_t)tok * 256 + (cb - 3072), acc[i][j], hh);
.Lp1_zcq:
	v_and_b32_e32 v165, 63, v181
	v_lshrrev_b32_e32 v167, 4, v165
	v_and_b32_e32 v168, 15, v165
	v_mul_u32_u24_e32 v166, 0x2200, v164
	v_mul_u32_u24_e32 v165, 0x110, v167
	v_add_u32_e32 v166, v166, v165
	v_add_u32_e32 v166, 0x8000, v166
	v_lshl_add_u32 v166, v168, 4, v166
	s_lshl_b32 s0, s53, 10
	s_sub_i32 s1, s54, 0xc00
	s_lshl_b32 s1, s1, 2
	s_add_i32 s0, s0, s1
	s_add_i32 s0, s0, 0x1699e000
	v_lshrrev_b32_e32 v170, 1, v164
	v_mul_u32_u24_e32 v170, 0x10000, v170
	v_mul_u32_u24_e32 v171, 0x400, v167
	v_add_u32_e32 v170, v170, v171
	v_and_b32_e32 v171, 1, v164
	v_mul_u32_u24_e32 v171, 0x100, v171
	v_lshl_add_u32 v171, v168, 4, v171
	v_add3_u32 v170, v170, v171, s0
	ds_write_b128 v138, v[48:51] offset:0
	ds_write_b128 v138, v[52:55] offset:32
	ds_write_b128 v138, v[56:59] offset:64
	ds_write_b128 v138, v[60:63] offset:96
	ds_write_b128 v138, v[32:35] offset:128
	ds_write_b128 v138, v[36:39] offset:160
	ds_write_b128 v138, v[40:43] offset:192
	ds_write_b128 v138, v[44:47] offset:224
	s_waitcnt lgkmcnt(0)
	ds_read_b128 v[32:35], v166 offset:0
	ds_read_b128 v[36:39], v166 offset:1088
	ds_read_b128 v[40:43], v166 offset:2176
	ds_read_b128 v[44:47], v166 offset:3264
	ds_read_b128 v[48:51], v166 offset:4352
	ds_read_b128 v[52:55], v166 offset:5440
	ds_read_b128 v[56:59], v166 offset:6528
	ds_read_b128 v[60:63], v166 offset:7616
	s_waitcnt lgkmcnt(7)
	global_store_dwordx4 v170, v[32:35], s[96:97]
	v_add_u32_e32 v170, 0x1000, v170
	s_waitcnt lgkmcnt(6)
	global_store_dwordx4 v170, v[36:39], s[96:97]
	v_add_u32_e32 v170, 0x1000, v170
	s_waitcnt lgkmcnt(5)
	global_store_dwordx4 v170, v[40:43], s[96:97]
	v_add_u32_e32 v170, 0x1000, v170
	s_waitcnt lgkmcnt(4)
	global_store_dwordx4 v170, v[44:47], s[96:97]
	v_add_u32_e32 v170, 0x1000, v170
	s_waitcnt lgkmcnt(3)
	global_store_dwordx4 v170, v[48:51], s[96:97]
	v_add_u32_e32 v170, 0x1000, v170
	s_waitcnt lgkmcnt(2)
	global_store_dwordx4 v170, v[52:55], s[96:97]
	v_add_u32_e32 v170, 0x1000, v170
	s_waitcnt lgkmcnt(1)
	global_store_dwordx4 v170, v[56:59], s[96:97]
	v_add_u32_e32 v170, 0x1000, v170
	s_waitcnt lgkmcnt(0)
	global_store_dwordx4 v170, v[60:63], s[96:97]
	v_add_u32_e32 v170, 0x1000, v170
	ds_write_b128 v138, v[16:19] offset:0
	ds_write_b128 v138, v[20:23] offset:32
	ds_write_b128 v138, v[24:27] offset:64
	ds_write_b128 v138, v[28:31] offset:96
	ds_write_b128 v138, v[0:3] offset:128
	ds_write_b128 v138, v[4:7] offset:160
	ds_write_b128 v138, v[8:11] offset:192
	ds_write_b128 v138, v[12:15] offset:224
	s_waitcnt lgkmcnt(0)
	ds_read_b128 v[0:3], v166 offset:0
	ds_read_b128 v[4:7], v166 offset:1088
	ds_read_b128 v[8:11], v166 offset:2176
	ds_read_b128 v[12:15], v166 offset:3264
	ds_read_b128 v[16:19], v166 offset:4352
	ds_read_b128 v[20:23], v166 offset:5440
	ds_read_b128 v[24:27], v166 offset:6528
	ds_read_b128 v[28:31], v166 offset:7616
	s_waitcnt lgkmcnt(7)
	global_store_dwordx4 v170, v[0:3], s[96:97]
	v_add_u32_e32 v170, 0x1000, v170
	s_waitcnt lgkmcnt(6)
	global_store_dwordx4 v170, v[4:7], s[96:97]
	v_add_u32_e32 v170, 0x1000, v170
	s_waitcnt lgkmcnt(5)
	global_store_dwordx4 v170, v[8:11], s[96:97]
	v_add_u32_e32 v170, 0x1000, v170
	s_waitcnt lgkmcnt(4)
	global_store_dwordx4 v170, v[12:15], s[96:97]
	v_add_u32_e32 v170, 0x1000, v170
	s_waitcnt lgkmcnt(3)
	global_store_dwordx4 v170, v[16:19], s[96:97]
	v_add_u32_e32 v170, 0x1000, v170
	s_waitcnt lgkmcnt(2)
	global_store_dwordx4 v170, v[20:23], s[96:97]
	v_add_u32_e32 v170, 0x1000, v170
	s_waitcnt lgkmcnt(1)
	global_store_dwordx4 v170, v[24:27], s[96:97]
	v_add_u32_e32 v170, 0x1000, v170
	s_waitcnt lgkmcnt(0)
	global_store_dwordx4 v170, v[28:31], s[96:97]
	v_add_u32_e32 v170, 0x1000, v170
	s_branch .LBB0_260
; __device__ void phase_inproj(const Params& p, char* lds) {
;     ...
;         } else if (nt == 26) {
;           st_f32_sw((float*)(ws + F_ZCKV) + (size_t)tok * 128 + (cb - 3328), acc[i][j], hh);
.Lp1_zckv:
	v_and_b32_e32 v165, 63, v181
	v_lshrrev_b32_e32 v167, 4, v165
	v_and_b32_e32 v168, 15, v165
	v_mul_u32_u24_e32 v166, 0x2200, v164
	v_mul_u32_u24_e32 v165, 0x110, v167
	v_add_u32_e32 v166, v166, v165
	v_add_u32_e32 v166, 0x8000, v166
	v_lshl_add_u32 v166, v168, 4, v166
	s_lshl_b32 s0, s53, 9
	s_add_i32 s0, s0, 0x18a1e000
	v_lshrrev_b32_e32 v170, 1, v164
	v_mul_u32_u24_e32 v170, 0x8000, v170
	v_mul_u32_u24_e32 v171, 0x200, v167
	v_add_u32_e32 v170, v170, v171
	v_and_b32_e32 v171, 1, v164
	v_mul_u32_u24_e32 v171, 0x100, v171
	v_lshl_add_u32 v171, v168, 4, v171
	v_add3_u32 v170, v170, v171, s0
	ds_write_b128 v138, v[48:51] offset:0
	ds_write_b128 v138, v[52:55] offset:32
	ds_write_b128 v138, v[56:59] offset:64
	ds_write_b128 v138, v[60:63] offset:96
	ds_write_b128 v138, v[32:35] offset:128
	ds_write_b128 v138, v[36:39] offset:160
	ds_write_b128 v138, v[40:43] offset:192
	ds_write_b128 v138, v[44:47] offset:224
	s_waitcnt lgkmcnt(0)
	ds_read_b128 v[32:35], v166 offset:0
	ds_read_b128 v[36:39], v166 offset:1088
	ds_read_b128 v[40:43], v166 offset:2176
	ds_read_b128 v[44:47], v166 offset:3264
	ds_read_b128 v[48:51], v166 offset:4352
	ds_read_b128 v[52:55], v166 offset:5440
	ds_read_b128 v[56:59], v166 offset:6528
	ds_read_b128 v[60:63], v166 offset:7616
	s_waitcnt lgkmcnt(7)
	global_store_dwordx4 v170, v[32:35], s[96:97]
	v_add_u32_e32 v170, 0x800, v170
	s_waitcnt lgkmcnt(6)
	global_store_dwordx4 v170, v[36:39], s[96:97]
	v_add_u32_e32 v170, 0x800, v170
	s_waitcnt lgkmcnt(5)
	global_store_dwordx4 v170, v[40:43], s[96:97]
	v_add_u32_e32 v170, 0x800, v170
	s_waitcnt lgkmcnt(4)
	global_store_dwordx4 v170, v[44:47], s[96:97]
	v_add_u32_e32 v170, 0x800, v170
	s_waitcnt lgkmcnt(3)
	global_store_dwordx4 v170, v[48:51], s[96:97]
	v_add_u32_e32 v170, 0x800, v170
	s_waitcnt lgkmcnt(2)
	global_store_dwordx4 v170, v[52:55], s[96:97]
	v_add_u32_e32 v170, 0x800, v170
	s_waitcnt lgkmcnt(1)
	global_store_dwordx4 v170, v[56:59], s[96:97]
	v_add_u32_e32 v170, 0x800, v170
	s_waitcnt lgkmcnt(0)
	global_store_dwordx4 v170, v[60:63], s[96:97]
	v_add_u32_e32 v170, 0x800, v170
	ds_write_b128 v138, v[16:19] offset:0
	ds_write_b128 v138, v[20:23] offset:32
	ds_write_b128 v138, v[24:27] offset:64
	ds_write_b128 v138, v[28:31] offset:96
	ds_write_b128 v138, v[0:3] offset:128
	ds_write_b128 v138, v[4:7] offset:160
	ds_write_b128 v138, v[8:11] offset:192
	ds_write_b128 v138, v[12:15] offset:224
	s_waitcnt lgkmcnt(0)
	ds_read_b128 v[0:3], v166 offset:0
	ds_read_b128 v[4:7], v166 offset:1088
	ds_read_b128 v[8:11], v166 offset:2176
	ds_read_b128 v[12:15], v166 offset:3264
	ds_read_b128 v[16:19], v166 offset:4352
	ds_read_b128 v[20:23], v166 offset:5440
	ds_read_b128 v[24:27], v166 offset:6528
	ds_read_b128 v[28:31], v166 offset:7616
	s_waitcnt lgkmcnt(7)
	global_store_dwordx4 v170, v[0:3], s[96:97]
	v_add_u32_e32 v170, 0x800, v170
	s_waitcnt lgkmcnt(6)
	global_store_dwordx4 v170, v[4:7], s[96:97]
	v_add_u32_e32 v170, 0x800, v170
	s_waitcnt lgkmcnt(5)
	global_store_dwordx4 v170, v[8:11], s[96:97]
	v_add_u32_e32 v170, 0x800, v170
	s_waitcnt lgkmcnt(4)
	global_store_dwordx4 v170, v[12:15], s[96:97]
	v_add_u32_e32 v170, 0x800, v170
	s_waitcnt lgkmcnt(3)
	global_store_dwordx4 v170, v[16:19], s[96:97]
	v_add_u32_e32 v170, 0x800, v170
	s_waitcnt lgkmcnt(2)
	global_store_dwordx4 v170, v[20:23], s[96:97]
	v_add_u32_e32 v170, 0x800, v170
	s_waitcnt lgkmcnt(1)
	global_store_dwordx4 v170, v[24:27], s[96:97]
	v_add_u32_e32 v170, 0x800, v170
	s_waitcnt lgkmcnt(0)
	global_store_dwordx4 v170, v[28:31], s[96:97]
	v_add_u32_e32 v170, 0x800, v170
	s_branch .LBB0_260

; __device__ void phase_peer_q(const Params& p, char* lds) {
;     ...
; #pragma unroll
;     for (int i = 0; i < 2; ++i)
; #pragma unroll
;       for (int j = 0; j < 2; ++j) {
;         const int tok = m0 + wr * 64 + i * 32 + l31; const int cb = n0 + wc * 64 + j * 32;
;         st_bf16_sw(pq + (size_t)tok * LDH + cb, acc[i][j], hh, 1.f);
;       }
.LBB0_1018:
	v_and_b32_e32 v119, 63, v181
	v_lshrrev_b32_e32 v118, 6, v181
	v_and_b32_e32 v114, 31, v119
	v_lshrrev_b32_e32 v115, 5, v119
	v_mul_u32_u24_e32 v114, 0x110, v114
	v_lshlrev_b32_e32 v115, 4, v115
	v_mul_u32_u24_e32 v116, 0x2200, v118
	v_add3_u32 v114, v114, v115, v116
	v_add_u32_e32 v114, 0x8000, v114
	v_add_u32_e32 v115, 0x8000, v116
	v_lshrrev_b32_e32 v116, 3, v119
	v_and_b32_e32 v117, 7, v119
	v_mul_u32_u24_e32 v119, 0x110, v116
	v_add_u32_e32 v115, v115, v119
	v_lshl_add_u32 v115, v117, 5, v115
	s_mul_i32 s1, s3, 0x880
	s_lshl_b32 s14, s25, 1
	s_add_i32 s1, s1, s14
	s_add_i32 s1, s1, 0x166e000
	v_lshrrev_b32_e32 v121, 1, v118
	v_mul_u32_u24_e32 v121, 0x22000, v121
	v_mul_u32_u24_e32 v122, 0x880, v116
	v_add_u32_e32 v121, v121, v122
	v_and_b32_e32 v122, 1, v118
	v_lshlrev_b32_e32 v122, 7, v122
	v_lshl_add_u32 v122, v117, 4, v122
	v_add3_u32 v120, v121, v122, s1
	ds_write_b128 v114, v[48:51] offset:0
	ds_write_b128 v114, v[52:55] offset:32
	ds_write_b128 v114, v[56:59] offset:64
	ds_write_b128 v114, v[60:63] offset:96
	ds_write_b128 v114, v[32:35] offset:128
	ds_write_b128 v114, v[36:39] offset:160
	ds_write_b128 v114, v[40:43] offset:192
	ds_write_b128 v114, v[44:47] offset:224
	s_waitcnt lgkmcnt(0)
	ds_read_b128 v[32:35], v115 offset:0
	ds_read_b128 v[36:39], v115 offset:16
	ds_read_b128 v[40:43], v115 offset:2176
	ds_read_b128 v[44:47], v115 offset:2192
	ds_read_b128 v[48:51], v115 offset:4352
	ds_read_b128 v[52:55], v115 offset:4368
	ds_read_b128 v[56:59], v115 offset:6528
	ds_read_b128 v[60:63], v115 offset:6544
	s_waitcnt lgkmcnt(6)
	v_cvt_pk_bf16_f32 v32, v32, v33
	v_cvt_pk_bf16_f32 v33, v34, v35
	v_cvt_pk_bf16_f32 v34, v36, v37
	v_cvt_pk_bf16_f32 v35, v38, v39
	global_store_dwordx4 v120, v[32:35], s[96:97]
	v_add_u32_e32 v120, 0x4400, v120
	s_waitcnt lgkmcnt(4)
	v_cvt_pk_bf16_f32 v40, v40, v41
	v_cvt_pk_bf16_f32 v41, v42, v43
	v_cvt_pk_bf16_f32 v42, v44, v45
	v_cvt_pk_bf16_f32 v43, v46, v47
	global_store_dwordx4 v120, v[40:43], s[96:97]
	v_add_u32_e32 v120, 0x4400, v120
	s_waitcnt lgkmcnt(2)
	v_cvt_pk_bf16_f32 v48, v48, v49
	v_cvt_pk_bf16_f32 v49, v50, v51
	v_cvt_pk_bf16_f32 v50, v52, v53
	v_cvt_pk_bf16_f32 v51, v54, v55
	global_store_dwordx4 v120, v[48:51], s[96:97]
	v_add_u32_e32 v120, 0x4400, v120
	s_waitcnt lgkmcnt(0)
	v_cvt_pk_bf16_f32 v56, v56, v57
	v_cvt_pk_bf16_f32 v57, v58, v59
	v_cvt_pk_bf16_f32 v58, v60, v61
	v_cvt_pk_bf16_f32 v59, v62, v63
	global_store_dwordx4 v120, v[56:59], s[96:97]
	v_add_u32_e32 v120, 0x4400, v120
	ds_write_b128 v114, v[16:19] offset:0
	ds_write_b128 v114, v[20:23] offset:32
	ds_write_b128 v114, v[24:27] offset:64
	ds_write_b128 v114, v[28:31] offset:96
	ds_write_b128 v114, v[0:3] offset:128
	ds_write_b128 v114, v[4:7] offset:160
	ds_write_b128 v114, v[8:11] offset:192
	ds_write_b128 v114, v[12:15] offset:224
	s_waitcnt lgkmcnt(0)
	ds_read_b128 v[0:3], v115 offset:0
	ds_read_b128 v[4:7], v115 offset:16
	ds_read_b128 v[8:11], v115 offset:2176
	ds_read_b128 v[12:15], v115 offset:2192
	ds_read_b128 v[16:19], v115 offset:4352
	ds_read_b128 v[20:23], v115 offset:4368
	ds_read_b128 v[24:27], v115 offset:6528
	ds_read_b128 v[28:31], v115 offset:6544
	s_waitcnt lgkmcnt(6)
	v_cvt_pk_bf16_f32 v0, v0, v1
	v_cvt_pk_bf16_f32 v1, v2, v3
	v_cvt_pk_bf16_f32 v2, v4, v5
	v_cvt_pk_bf16_f32 v3, v6, v7
	global_store_dwordx4 v120, v[0:3], s[96:97]
	v_add_u32_e32 v120, 0x4400, v120
	s_waitcnt lgkmcnt(4)
	v_cvt_pk_bf16_f32 v8, v8, v9
	v_cvt_pk_bf16_f32 v9, v10, v11
	v_cvt_pk_bf16_f32 v10, v12, v13
	v_cvt_pk_bf16_f32 v11, v14, v15
	global_store_dwordx4 v120, v[8:11], s[96:97]
	v_add_u32_e32 v120, 0x4400, v120
	s_waitcnt lgkmcnt(2)
	v_cvt_pk_bf16_f32 v16, v16, v17
	v_cvt_pk_bf16_f32 v17, v18, v19
	v_cvt_pk_bf16_f32 v18, v20, v21
	v_cvt_pk_bf16_f32 v19, v22, v23
	global_store_dwordx4 v120, v[16:19], s[96:97]
	v_add_u32_e32 v120, 0x4400, v120
	s_waitcnt lgkmcnt(0)
	v_cvt_pk_bf16_f32 v24, v24, v25
	v_cvt_pk_bf16_f32 v25, v26, v27
	v_cvt_pk_bf16_f32 v26, v28, v29
	v_cvt_pk_bf16_f32 v27, v30, v31
	global_store_dwordx4 v120, v[24:27], s[96:97]
	s_add_i32 s2, s2, 1
	s_mul_i32 s0, s2, s16
	s_add_i32 s0, s0, s73
	s_cmp_lt_i32 s0, s19
	s_cbranch_scc0 .LBB0_1026
